# v035 + w_in GEMM bias vectors fetched ahead of the K-loop into spare registers (no load + vmcnt drain at the epilogue start)
# baseline (speedup 1.0000x reference)
.LBB0_277:
	v_mbcnt_lo_u32_b32 v0, -1, 0
	v_mbcnt_hi_u32_b32 v0, -1, v0
	s_mov_b64 s[2:3], 0
	v_or_b32_e32 v152, s94, v0
	s_load_dword s0, s[90:91], 0xd8
	s_mov_b32 s1, s88
	v_mov_b32_e32 v4, v152
	s_mov_b32 s57, 0
	s_waitcnt lgkmcnt(0)
	s_cmpk_gt_u32 s1, 0x4c7
	v_readfirstlane_b32 s12, v4
	s_cbranch_scc1 .LBB0_291
	v_bfe_i32 v1, v4, 27, 1
	v_lshlrev_b32_e32 v0, 4, v4
	v_lshrrev_b32_e32 v1, 22, v1
	v_add_u32_e32 v1, v0, v1
	v_and_b32_e32 v1, 0xfffffc00, v1
	v_sub_u32_e32 v0, v0, v1
	v_lshrrev_b32_e32 v1, 4, v0
	v_bitop3_b32 v1, v1, v0, 32 bitop3:0x6c
	v_ashrrev_i32_e32 v0, 31, v0
	v_lshrrev_b32_e32 v0, 26, v0
	v_add_u32_e32 v0, v1, v0
	v_ashrrev_i32_e32 v5, 6, v0
	v_ashrrev_i32_e32 v0, 31, v4
	v_lshrrev_b32_e32 v0, 26, v0
	s_add_u32 s18, s86, s2
	v_add_u32_e32 v0, v4, v0
	s_addc_u32 s19, s87, s3
	v_ashrrev_i32_e32 v6, 6, v0
	s_add_u32 s13, s18, 0x8a33600
	v_lshlrev_b32_e32 v0, 3, v6
	s_addc_u32 s14, s19, 0
	v_and_b32_e32 v0, -16, v0
	s_add_u32 s15, s18, 0x4b600
	v_add_u32_e32 v0, v5, v0
	v_and_b32_e32 v2, 3, v5
	s_mov_b32 s2, 0xfffe0
	s_addc_u32 s16, s19, 0
	v_and_or_b32 v2, v0, s2, v2
	s_and_b32 s2, s1, 7
	s_lshr_b32 s3, s1, 3
	s_mulk_i32 s2, 0x99
	s_add_i32 s2, s2, s3
	s_mul_i32 s3, s2, 0xe38f
	s_lshr_b32 s3, s3, 24
	s_lshl_b32 s6, s3, 3
	s_and_b32 s7, s6, 0xfff8
	v_lshrrev_b32_e32 v3, 2, v0
	v_lshlrev_b32_e32 v7, 1, v0
	s_sub_i32 s7, 34, s7
	s_mulk_i32 s3, 0x120
	v_and_b32_e32 v3, 4, v3
	v_and_b32_e32 v7, 24, v7
	s_min_u32 s7, s7, 8
	s_sub_i32 s8, s2, s3
	v_or3_b32 v2, v2, v3, v7
	v_mul_i32_i24_e32 v7, 64, v5
	s_and_b32 s2, s8, 0xffff
	v_cvt_f32_ubyte0_e32 v9, s7
	v_sub_u32_e32 v1, v1, v7
	v_mov_b32_e32 v7, 1
	v_cvt_f32_u32_e32 v8, s2
	v_rcp_iflag_f32_e32 v10, v9
	v_lshlrev_b32_e32 v3, 5, v6
	v_ashrrev_i16_sdwa v1, v7, sext(v1) dst_sel:DWORD dst_unused:UNUSED_PAD src0_sel:DWORD src1_sel:BYTE_0
	v_and_b32_e32 v3, 32, v3
	v_bfe_i32 v7, v1, 0, 16
	v_add_lshl_u32 v1, v3, v7, 1
	v_lshl_add_u32 v144, v2, 12, v1
	v_mul_f32_e32 v2, v8, v10
	v_trunc_f32_e32 v2, v2
	v_cvt_u32_f32_e32 v3, v2
	s_ashr_i32 s36, s12, 6
	v_lshl_add_u32 v146, v0, 12, v1
	v_fma_f32 v0, -v2, v9, v8
	s_ashr_i32 s17, s12, 8
	s_lshl_b32 s20, s36, 10
	v_cmp_ge_f32_e64 s[2:3], |v0|, v9
	v_readfirstlane_b32 s9, v3
	s_cmp_lg_u64 s[2:3], 0
	s_addc_u32 s9, s9, 0
	s_mul_i32 s2, s9, s7
	s_sub_i32 s2, s8, s2
	s_add_i32 s2, s2, s6
	s_and_b32 s56, s2, 0xffff
	s_lshl_b64 s[2:3], s[56:57], 20
	s_add_u32 s60, s13, s2
	s_addc_u32 s61, s14, s3
	s_and_b32 s58, s9, 0xffff
	s_mov_b32 s59, s57
	s_lshl_b64 s[2:3], s[58:59], 20
	s_add_u32 s62, s15, s2
	s_addc_u32 s63, s16, s3
	s_and_b32 s2, s36, 3
	s_lshl_b32 s2, s2, 5
	s_lshl_b32 s3, s58, 8
	s_add_i32 s2, s2, s3
	v_lshrrev_b32_e32 v226, 1, v152
	v_and_or_b32 v226, v226, 24, s2
	v_ashrrev_i32_e32 v227, 31, v226
	s_add_u32 s6, s18, 0x219b3600
	s_addc_u32 s7, s19, 0
	v_lshl_add_u64 v[226:227], v[226:227], 2, s[6:7]
	global_load_dwordx4 v[222:225], v[226:227], off
	global_load_dwordx4 v[218:221], v[226:227], off offset:16
	global_load_dwordx4 v[214:217], v[226:227], off offset:512
	global_load_dwordx4 v[210:213], v[226:227], off offset:528
	v_mov_b32_e32 v145, 0
	s_add_i32 s21, s20, 0
	v_lshl_add_u64 v[0:1], s[62:63], 0, v[144:145]
	s_add_i32 m0, s21, 0x10000
	s_mov_b64 s[2:3], 0x40000
	global_load_lds_dwordx4 v144, s[62:63]
	v_lshl_add_u64 v[2:3], v[0:1], 0, s[2:3]
	s_add_i32 m0, s21, 0x12000
	v_mov_b32_e32 v147, v145
	global_load_lds_dwordx4 v[2:3], off
	v_lshl_add_u64 v[2:3], s[60:61], 0, v[146:147]
	s_mov_b32 m0, s21
	s_add_i32 s28, s21, 0x2000
	global_load_lds_dwordx4 v146, s[60:61]
	v_lshl_add_u64 v[8:9], v[2:3], 0, s[2:3]
	s_mov_b32 m0, s28
	s_mov_b64 s[6:7], 0x80000
	global_load_lds_dwordx4 v[8:9], off
	v_lshl_add_u64 v[8:9], v[0:1], 0, s[6:7]
	s_add_i32 m0, s21, 0x14000
	s_mov_b64 s[8:9], 0xc0000
	global_load_lds_dwordx4 v[8:9], off
	v_lshl_add_u64 v[8:9], v[0:1], 0, s[8:9]
	s_add_i32 m0, s21, 0x16000
	s_add_i32 s29, s21, 0x4000
	global_load_lds_dwordx4 v[8:9], off
	v_lshl_add_u64 v[8:9], v[2:3], 0, s[6:7]
	s_mov_b32 m0, s29
	s_add_i32 s30, s21, 0x6000
	global_load_lds_dwordx4 v[8:9], off
	v_lshl_add_u64 v[8:9], v[2:3], 0, s[8:9]
	s_mov_b32 m0, s30
	s_cmp_lg_u32 s17, 1
	global_load_lds_dwordx4 v[8:9], off
	s_cbranch_scc1 .LBB0_280
	s_barrier

.LBB0_285:
	ds_read_b128 v[128:131], v154
	ds_read_b128 v[132:135], v154 offset:1024
	ds_read_b128 v[136:139], v154 offset:2048
	ds_read_b128 v[140:143], v154 offset:3072
	s_add_u32 s45, s60, 0xfff80080
	s_addc_u32 s46, s61, -1
	s_cmp_eq_u32 s44, 28
	s_cselect_b32 s47, s53, s46
	s_cselect_b32 s46, s52, s45
	s_cselect_b32 s49, s55, s43
	s_cselect_b32 s48, s54, s42
	v_lshl_add_u64 v[150:151], s[60:61], 0, v[148:149]
	s_add_i32 m0, s21, 0xc000
	ds_read_b128 v[158:161], v155
	ds_read_b128 v[162:165], v155 offset:1024
	ds_read_b128 v[166:169], v155 offset:2048
	ds_read_b128 v[170:173], v155 offset:3072
	ds_read_b128 v[174:177], v155 offset:4096
	ds_read_b128 v[178:181], v155 offset:5120
	ds_read_b128 v[182:185], v155 offset:6144
	ds_read_b128 v[186:189], v155 offset:7168
	global_load_lds_dwordx4 v[150:151], off
	v_lshl_add_u64 v[150:151], v[150:151], 0, s[2:3]
	s_add_i32 m0, s21, 0xe000
	s_nop 0
	global_load_lds_dwordx4 v[150:151], off
	s_waitcnt lgkmcnt(8)
	s_barrier
	s_waitcnt lgkmcnt(0)
	s_waitcnt lgkmcnt(0)
	v_mfma_f32_16x16x32_bf16 v[124:127], v[128:131], v[158:161], v[124:127]
	v_mfma_f32_16x16x32_bf16 v[120:123], v[136:139], v[158:161], v[120:123]
	v_mfma_f32_16x16x32_bf16 v[116:119], v[128:131], v[166:169], v[116:119]
	v_mfma_f32_16x16x32_bf16 v[112:115], v[136:139], v[166:169], v[112:115]
	v_mfma_f32_16x16x32_bf16 v[108:111], v[128:131], v[174:177], v[108:111]
	v_mfma_f32_16x16x32_bf16 v[100:103], v[136:139], v[174:177], v[100:103]
	v_mfma_f32_16x16x32_bf16 v[92:95], v[128:131], v[182:185], v[92:95]
	v_mfma_f32_16x16x32_bf16 v[84:87], v[136:139], v[182:185], v[84:87]
	v_mfma_f32_16x16x32_bf16 v[124:127], v[132:135], v[162:165], v[124:127]
	v_mfma_f32_16x16x32_bf16 v[120:123], v[140:143], v[162:165], v[120:123]
	v_mfma_f32_16x16x32_bf16 v[116:119], v[132:135], v[170:173], v[116:119]
	v_mfma_f32_16x16x32_bf16 v[112:115], v[140:143], v[170:173], v[112:115]
	v_mfma_f32_16x16x32_bf16 v[108:111], v[132:135], v[178:181], v[108:111]
	v_mfma_f32_16x16x32_bf16 v[100:103], v[140:143], v[178:181], v[100:103]
	v_mfma_f32_16x16x32_bf16 v[92:95], v[132:135], v[186:189], v[92:95]
	v_mfma_f32_16x16x32_bf16 v[84:87], v[140:143], v[186:189], v[84:87]
	s_barrier
	s_add_i32 s45, s39, s20
	v_lshl_add_u64 v[150:151], s[48:49], 0, v[144:145]
	s_mov_b32 m0, s45
	ds_read_b128 v[190:193], v156
	ds_read_b128 v[194:197], v156 offset:1024
	ds_read_b128 v[198:201], v156 offset:2048
	ds_read_b128 v[202:205], v156 offset:3072
	global_load_lds_dwordx4 v[150:151], off
	v_lshl_add_u64 v[206:207], v[150:151], 0, s[2:3]
	s_add_i32 m0, s45, 0x2000
	s_nop 0
	global_load_lds_dwordx4 v[206:207], off
	s_barrier
	s_waitcnt lgkmcnt(0)
	s_waitcnt lgkmcnt(0)
	v_mfma_f32_16x16x32_bf16 v[104:107], v[190:193], v[158:161], v[104:107]
	v_mfma_f32_16x16x32_bf16 v[96:99], v[198:201], v[158:161], v[96:99]
	v_mfma_f32_16x16x32_bf16 v[88:91], v[190:193], v[166:169], v[88:91]
	v_mfma_f32_16x16x32_bf16 v[80:83], v[198:201], v[166:169], v[80:83]
	v_mfma_f32_16x16x32_bf16 v[76:79], v[190:193], v[174:177], v[76:79]
	v_mfma_f32_16x16x32_bf16 v[72:75], v[198:201], v[174:177], v[72:75]
	v_mfma_f32_16x16x32_bf16 v[68:71], v[190:193], v[182:185], v[68:71]
	v_mfma_f32_16x16x32_bf16 v[64:67], v[198:201], v[182:185], v[64:67]
	v_mfma_f32_16x16x32_bf16 v[104:107], v[194:197], v[162:165], v[104:107]
	v_mfma_f32_16x16x32_bf16 v[96:99], v[202:205], v[162:165], v[96:99]
	v_mfma_f32_16x16x32_bf16 v[88:91], v[194:197], v[170:173], v[88:91]
	v_mfma_f32_16x16x32_bf16 v[80:83], v[202:205], v[170:173], v[80:83]
	v_mfma_f32_16x16x32_bf16 v[76:79], v[194:197], v[178:181], v[76:79]
	v_mfma_f32_16x16x32_bf16 v[72:75], v[202:205], v[178:181], v[72:75]
	v_mfma_f32_16x16x32_bf16 v[68:71], v[194:197], v[186:189], v[68:71]
	v_mfma_f32_16x16x32_bf16 v[64:67], v[202:205], v[186:189], v[64:67]
	s_mov_b32 m0, s21
	v_lshl_add_u64 v[206:207], s[46:47], 0, v[146:147]
	s_barrier
	ds_read_b128 v[158:161], v155 offset:16384
	ds_read_b128 v[162:165], v155 offset:17408
	ds_read_b128 v[166:169], v155 offset:18432
	ds_read_b128 v[170:173], v155 offset:19456
	ds_read_b128 v[174:177], v155 offset:20480
	ds_read_b128 v[178:181], v155 offset:21504
	ds_read_b128 v[182:185], v155 offset:22528
	ds_read_b128 v[186:189], v155 offset:23552
	global_load_lds_dwordx4 v[206:207], off
	v_lshl_add_u64 v[208:209], v[206:207], 0, s[2:3]
	s_mov_b32 m0, s28
	s_nop 0
	global_load_lds_dwordx4 v[208:209], off
	s_barrier
	s_waitcnt lgkmcnt(0)
	s_waitcnt lgkmcnt(0)
	v_mfma_f32_16x16x32_bf16 v[60:63], v[128:131], v[158:161], v[60:63]
	v_mfma_f32_16x16x32_bf16 v[56:59], v[136:139], v[158:161], v[56:59]
	v_mfma_f32_16x16x32_bf16 v[48:51], v[128:131], v[166:169], v[48:51]
	v_mfma_f32_16x16x32_bf16 v[40:43], v[136:139], v[166:169], v[40:43]
	v_mfma_f32_16x16x32_bf16 v[32:35], v[128:131], v[174:177], v[32:35]
	v_mfma_f32_16x16x32_bf16 v[24:27], v[136:139], v[174:177], v[24:27]
	v_mfma_f32_16x16x32_bf16 v[16:19], v[128:131], v[182:185], v[16:19]
	v_mfma_f32_16x16x32_bf16 v[8:11], v[136:139], v[182:185], v[8:11]
	v_mfma_f32_16x16x32_bf16 v[60:63], v[132:135], v[162:165], v[60:63]
	v_mfma_f32_16x16x32_bf16 v[56:59], v[140:143], v[162:165], v[56:59]
	v_mfma_f32_16x16x32_bf16 v[48:51], v[132:135], v[170:173], v[48:51]
	v_mfma_f32_16x16x32_bf16 v[40:43], v[140:143], v[170:173], v[40:43]
	v_mfma_f32_16x16x32_bf16 v[32:35], v[132:135], v[178:181], v[32:35]
	v_mfma_f32_16x16x32_bf16 v[24:27], v[140:143], v[178:181], v[24:27]
	v_mfma_f32_16x16x32_bf16 v[16:19], v[132:135], v[186:189], v[16:19]
	v_mfma_f32_16x16x32_bf16 v[8:11], v[140:143], v[186:189], v[8:11]
	s_barrier
	s_add_i32 s45, s40, s20
	v_lshl_add_u64 v[128:129], v[150:151], 0, s[6:7]
	s_mov_b32 m0, s45
	s_nop 0
	global_load_lds_dwordx4 v[128:129], off
	v_lshl_add_u64 v[128:129], v[150:151], 0, s[8:9]
	s_add_i32 m0, s45, 0x2000
	s_nop 0
	global_load_lds_dwordx4 v[128:129], off
	s_waitcnt vmcnt(6)
	s_barrier
	v_mfma_f32_16x16x32_bf16 v[52:55], v[190:193], v[158:161], v[52:55]
	v_mfma_f32_16x16x32_bf16 v[44:47], v[198:201], v[158:161], v[44:47]
	v_mfma_f32_16x16x32_bf16 v[36:39], v[190:193], v[166:169], v[36:39]
	v_mfma_f32_16x16x32_bf16 v[28:31], v[198:201], v[166:169], v[28:31]
	v_mfma_f32_16x16x32_bf16 v[20:23], v[190:193], v[174:177], v[20:23]
	v_mfma_f32_16x16x32_bf16 v[12:15], v[198:201], v[174:177], v[12:15]
	v_mfma_f32_16x16x32_bf16 v[4:7], v[190:193], v[182:185], v[4:7]
	v_mfma_f32_16x16x32_bf16 v[0:3], v[198:201], v[182:185], v[0:3]
	v_mfma_f32_16x16x32_bf16 v[52:55], v[194:197], v[162:165], v[52:55]
	v_mfma_f32_16x16x32_bf16 v[44:47], v[202:205], v[162:165], v[44:47]
	v_mfma_f32_16x16x32_bf16 v[36:39], v[194:197], v[170:173], v[36:39]
	v_mfma_f32_16x16x32_bf16 v[28:31], v[202:205], v[170:173], v[28:31]
	v_mfma_f32_16x16x32_bf16 v[20:23], v[194:197], v[178:181], v[20:23]
	v_mfma_f32_16x16x32_bf16 v[12:15], v[202:205], v[178:181], v[12:15]
	v_mfma_f32_16x16x32_bf16 v[4:7], v[194:197], v[186:189], v[4:7]
	v_mfma_f32_16x16x32_bf16 v[0:3], v[202:205], v[186:189], v[0:3]
	s_add_i32 s45, 0, 0x18000
	v_add_u32_e32 v140, s45, v153
	s_barrier
	ds_read_b128 v[128:131], v140
	ds_read_b128 v[132:135], v140 offset:1024
	ds_read_b128 v[136:139], v140 offset:2048
	ds_read_b128 v[140:143], v140 offset:3072
	s_mov_b32 m0, s29
	v_lshl_add_u64 v[190:191], v[206:207], 0, s[6:7]
	ds_read_b128 v[158:161], v155 offset:32768
	ds_read_b128 v[162:165], v155 offset:33792
	ds_read_b128 v[166:169], v155 offset:34816
	ds_read_b128 v[170:173], v155 offset:35840
	ds_read_b128 v[174:177], v155 offset:36864
	ds_read_b128 v[178:181], v155 offset:37888
	ds_read_b128 v[182:185], v155 offset:38912
	ds_read_b128 v[186:189], v155 offset:39936
	global_load_lds_dwordx4 v[190:191], off
	v_lshl_add_u64 v[190:191], v[206:207], 0, s[8:9]
	s_mov_b32 m0, s30
	s_nop 0
	global_load_lds_dwordx4 v[190:191], off
	s_waitcnt lgkmcnt(8)
	s_barrier
	s_waitcnt lgkmcnt(0)
	s_waitcnt lgkmcnt(0)
	v_mfma_f32_16x16x32_bf16 v[124:127], v[128:131], v[158:161], v[124:127]
	v_mfma_f32_16x16x32_bf16 v[120:123], v[136:139], v[158:161], v[120:123]
	v_mfma_f32_16x16x32_bf16 v[116:119], v[128:131], v[166:169], v[116:119]
	v_mfma_f32_16x16x32_bf16 v[112:115], v[136:139], v[166:169], v[112:115]
	v_mfma_f32_16x16x32_bf16 v[108:111], v[128:131], v[174:177], v[108:111]
	v_mfma_f32_16x16x32_bf16 v[100:103], v[136:139], v[174:177], v[100:103]
	v_mfma_f32_16x16x32_bf16 v[92:95], v[128:131], v[182:185], v[92:95]
	v_mfma_f32_16x16x32_bf16 v[84:87], v[136:139], v[182:185], v[84:87]
	v_mfma_f32_16x16x32_bf16 v[124:127], v[132:135], v[162:165], v[124:127]
	v_mfma_f32_16x16x32_bf16 v[120:123], v[140:143], v[162:165], v[120:123]
	v_mfma_f32_16x16x32_bf16 v[116:119], v[132:135], v[170:173], v[116:119]
	v_mfma_f32_16x16x32_bf16 v[112:115], v[140:143], v[170:173], v[112:115]
	v_mfma_f32_16x16x32_bf16 v[108:111], v[132:135], v[178:181], v[108:111]
	v_mfma_f32_16x16x32_bf16 v[100:103], v[140:143], v[178:181], v[100:103]
	v_mfma_f32_16x16x32_bf16 v[92:95], v[132:135], v[186:189], v[92:95]
	v_mfma_f32_16x16x32_bf16 v[84:87], v[140:143], v[186:189], v[84:87]
	s_barrier
	s_add_i32 s46, 0, 0x1c000
	s_add_i32 s45, s45, s20
	v_add_u32_e32 v157, s46, v153
	v_lshl_add_u64 v[208:209], v[150:151], 0, s[22:23]
	s_mov_b32 m0, s45
	ds_read_b128 v[190:193], v157
	ds_read_b128 v[194:197], v157 offset:1024
	ds_read_b128 v[198:201], v157 offset:2048
	ds_read_b128 v[202:205], v157 offset:3072
	global_load_lds_dwordx4 v[208:209], off
	v_lshl_add_u64 v[208:209], v[150:151], 0, s[24:25]
	s_add_i32 m0, s45, 0x2000
	s_nop 0
	global_load_lds_dwordx4 v[208:209], off
	s_barrier
	s_waitcnt lgkmcnt(0)
	s_waitcnt lgkmcnt(0)
	v_mfma_f32_16x16x32_bf16 v[104:107], v[190:193], v[158:161], v[104:107]
	v_mfma_f32_16x16x32_bf16 v[96:99], v[198:201], v[158:161], v[96:99]
	v_mfma_f32_16x16x32_bf16 v[88:91], v[190:193], v[166:169], v[88:91]
	v_mfma_f32_16x16x32_bf16 v[80:83], v[198:201], v[166:169], v[80:83]
	v_mfma_f32_16x16x32_bf16 v[76:79], v[190:193], v[174:177], v[76:79]
	v_mfma_f32_16x16x32_bf16 v[72:75], v[198:201], v[174:177], v[72:75]
	v_mfma_f32_16x16x32_bf16 v[68:71], v[190:193], v[182:185], v[68:71]
	v_mfma_f32_16x16x32_bf16 v[64:67], v[198:201], v[182:185], v[64:67]
	v_mfma_f32_16x16x32_bf16 v[104:107], v[194:197], v[162:165], v[104:107]
	v_mfma_f32_16x16x32_bf16 v[96:99], v[202:205], v[162:165], v[96:99]
	v_mfma_f32_16x16x32_bf16 v[88:91], v[194:197], v[170:173], v[88:91]
	v_mfma_f32_16x16x32_bf16 v[80:83], v[202:205], v[170:173], v[80:83]
	v_mfma_f32_16x16x32_bf16 v[76:79], v[194:197], v[178:181], v[76:79]
	v_mfma_f32_16x16x32_bf16 v[72:75], v[202:205], v[178:181], v[72:75]
	v_mfma_f32_16x16x32_bf16 v[68:71], v[194:197], v[186:189], v[68:71]
	v_mfma_f32_16x16x32_bf16 v[64:67], v[202:205], v[186:189], v[64:67]
	s_mov_b32 m0, s31
	v_lshl_add_u64 v[208:209], v[206:207], 0, s[22:23]
	s_barrier
	ds_read_b128 v[158:161], v155 offset:49152
	ds_read_b128 v[162:165], v155 offset:50176
	ds_read_b128 v[166:169], v155 offset:51200
	ds_read_b128 v[170:173], v155 offset:52224
	ds_read_b128 v[174:177], v155 offset:53248
	ds_read_b128 v[178:181], v155 offset:54272
	ds_read_b128 v[182:185], v155 offset:55296
	ds_read_b128 v[186:189], v155 offset:56320
	global_load_lds_dwordx4 v[208:209], off
	v_lshl_add_u64 v[206:207], v[206:207], 0, s[24:25]
	s_mov_b32 m0, s33
	s_nop 0
	global_load_lds_dwordx4 v[206:207], off
	s_barrier
	s_waitcnt lgkmcnt(0)
	s_waitcnt lgkmcnt(0)
	v_mfma_f32_16x16x32_bf16 v[60:63], v[128:131], v[158:161], v[60:63]
	v_mfma_f32_16x16x32_bf16 v[56:59], v[136:139], v[158:161], v[56:59]
	v_mfma_f32_16x16x32_bf16 v[48:51], v[128:131], v[166:169], v[48:51]
	v_mfma_f32_16x16x32_bf16 v[40:43], v[136:139], v[166:169], v[40:43]
	v_mfma_f32_16x16x32_bf16 v[32:35], v[128:131], v[174:177], v[32:35]
	v_mfma_f32_16x16x32_bf16 v[24:27], v[136:139], v[174:177], v[24:27]
	v_mfma_f32_16x16x32_bf16 v[16:19], v[128:131], v[182:185], v[16:19]
	v_mfma_f32_16x16x32_bf16 v[8:11], v[136:139], v[182:185], v[8:11]
	v_mfma_f32_16x16x32_bf16 v[60:63], v[132:135], v[162:165], v[60:63]
	v_mfma_f32_16x16x32_bf16 v[56:59], v[140:143], v[162:165], v[56:59]
	v_mfma_f32_16x16x32_bf16 v[48:51], v[132:135], v[170:173], v[48:51]
	v_mfma_f32_16x16x32_bf16 v[40:43], v[140:143], v[170:173], v[40:43]
	v_mfma_f32_16x16x32_bf16 v[32:35], v[132:135], v[178:181], v[32:35]
	v_mfma_f32_16x16x32_bf16 v[24:27], v[140:143], v[178:181], v[24:27]
	v_mfma_f32_16x16x32_bf16 v[16:19], v[132:135], v[186:189], v[16:19]
	v_mfma_f32_16x16x32_bf16 v[8:11], v[140:143], v[186:189], v[8:11]
	s_barrier
	s_add_i32 s45, s46, s20
	v_lshl_add_u64 v[128:129], v[150:151], 0, s[26:27]
	s_mov_b32 m0, s45
	s_nop 0
	global_load_lds_dwordx4 v[128:129], off
	v_lshl_add_u64 v[128:129], v[150:151], 0, s[34:35]
	s_add_i32 m0, s45, 0x2000
	s_nop 0
	global_load_lds_dwordx4 v[128:129], off
	s_waitcnt vmcnt(6)
	s_barrier
	v_mfma_f32_16x16x32_bf16 v[52:55], v[190:193], v[158:161], v[52:55]
	v_mfma_f32_16x16x32_bf16 v[44:47], v[198:201], v[158:161], v[44:47]
	v_mfma_f32_16x16x32_bf16 v[36:39], v[190:193], v[166:169], v[36:39]
	v_mfma_f32_16x16x32_bf16 v[28:31], v[198:201], v[166:169], v[28:31]
	v_mfma_f32_16x16x32_bf16 v[20:23], v[190:193], v[174:177], v[20:23]
	v_mfma_f32_16x16x32_bf16 v[12:15], v[198:201], v[174:177], v[12:15]
	v_mfma_f32_16x16x32_bf16 v[4:7], v[190:193], v[182:185], v[4:7]
	v_mfma_f32_16x16x32_bf16 v[0:3], v[198:201], v[182:185], v[0:3]
	v_mfma_f32_16x16x32_bf16 v[52:55], v[194:197], v[162:165], v[52:55]
	v_mfma_f32_16x16x32_bf16 v[44:47], v[202:205], v[162:165], v[44:47]
	v_mfma_f32_16x16x32_bf16 v[36:39], v[194:197], v[170:173], v[36:39]
	v_mfma_f32_16x16x32_bf16 v[28:31], v[202:205], v[170:173], v[28:31]
	v_mfma_f32_16x16x32_bf16 v[20:23], v[194:197], v[178:181], v[20:23]
	v_mfma_f32_16x16x32_bf16 v[12:15], v[202:205], v[178:181], v[12:15]
	v_mfma_f32_16x16x32_bf16 v[4:7], v[194:197], v[186:189], v[4:7]
	v_mfma_f32_16x16x32_bf16 v[0:3], v[202:205], v[186:189], v[0:3]
	s_add_i32 s44, s44, 2
	s_add_u32 s60, s60, 0x100
	s_addc_u32 s61, s61, 0
	s_add_u32 s42, s42, 0x100
	s_addc_u32 s43, s43, 0
	s_cmp_gt_u32 s44, 29
	s_barrier
	s_cbranch_scc0 .LBB0_285
	v_mov_b32_e32 v157, v152
	s_mov_b32 s42, s36
	s_mov_b32 s43, s17
	s_lshl_b32 s44, s58, 8
	s_lshl_b32 s42, s42, 5
	s_add_i32 s42, s42, s44
	v_lshrrev_b32_e32 v128, 1, v157
	v_and_or_b32 v150, v128, 24, s42
	v_ashrrev_i32_e32 v151, 31, v150
	s_lshl_b32 s42, s56, 8
	v_and_or_b32 v157, v157, 15, s42
	v_lshl_add_u32 v157, s43, 6, v157
	v_lshl_add_u64 v[150:151], v[150:151], 1, s[10:11]
	v_mad_i64_i32 v[158:159], s[42:43], v157, s41, v[150:151]
	v_or_b32_e32 v160, 16, v157
	v_mad_i64_i32 v[160:161], s[42:43], v160, s41, v[150:151]
	v_or_b32_e32 v162, 32, v157
	v_mad_i64_i32 v[162:163], s[42:43], v162, s41, v[150:151]
	v_or_b32_e32 v168, 48, v157
	s_mov_b64 s[60:61], -1
	v_pk_add_f32 v[126:127], v[126:127], v[224:225]
	v_pk_add_f32 v[124:125], v[124:125], v[222:223]
	v_pk_add_f32 v[166:167], v[68:69], v[214:215]
	v_cvt_pk_bf16_f32 v68, v124, v125
	v_cvt_pk_bf16_f32 v69, v126, v127
	v_pk_add_f32 v[122:123], v[122:123], v[220:221]
	v_pk_add_f32 v[120:121], v[120:121], v[218:219]
	v_pk_add_f32 v[106:107], v[106:107], v[216:217]
	v_pk_add_f32 v[104:105], v[104:105], v[214:215]
	v_pk_add_f32 v[164:165], v[70:71], v[216:217]
	v_cvt_pk_bf16_f32 v70, v120, v121
	v_cvt_pk_bf16_f32 v71, v122, v123
	global_store_dwordx4 v[158:159], v[68:71], off
	v_pk_add_f32 v[98:99], v[98:99], v[212:213]
	v_pk_add_f32 v[96:97], v[96:97], v[210:211]
	v_cvt_pk_bf16_f32 v68, v104, v105
	v_cvt_pk_bf16_f32 v69, v106, v107
	v_pk_add_f32 v[118:119], v[118:119], v[224:225]
	v_pk_add_f32 v[116:117], v[116:117], v[222:223]
	v_cvt_pk_bf16_f32 v70, v96, v97
	v_cvt_pk_bf16_f32 v71, v98, v99
	global_store_dwordx4 v[158:159], v[68:71], off offset:256
	v_pk_add_f32 v[114:115], v[114:115], v[220:221]
	v_pk_add_f32 v[112:113], v[112:113], v[218:219]
	v_cvt_pk_bf16_f32 v68, v116, v117
	v_cvt_pk_bf16_f32 v69, v118, v119
	v_pk_add_f32 v[90:91], v[90:91], v[216:217]
	v_pk_add_f32 v[88:89], v[88:89], v[214:215]
	v_cvt_pk_bf16_f32 v70, v112, v113
	v_cvt_pk_bf16_f32 v71, v114, v115
	global_store_dwordx4 v[160:161], v[68:71], off
	v_pk_add_f32 v[82:83], v[82:83], v[212:213]
	v_pk_add_f32 v[80:81], v[80:81], v[210:211]
	v_cvt_pk_bf16_f32 v68, v88, v89
	v_cvt_pk_bf16_f32 v69, v90, v91
	v_pk_add_f32 v[110:111], v[110:111], v[224:225]
	v_pk_add_f32 v[108:109], v[108:109], v[222:223]
	v_cvt_pk_bf16_f32 v70, v80, v81
	v_cvt_pk_bf16_f32 v71, v82, v83
	global_store_dwordx4 v[160:161], v[68:71], off offset:256
	v_pk_add_f32 v[102:103], v[102:103], v[220:221]
	v_pk_add_f32 v[100:101], v[100:101], v[218:219]
	v_cvt_pk_bf16_f32 v68, v108, v109
	v_cvt_pk_bf16_f32 v69, v110, v111
	v_pk_add_f32 v[78:79], v[78:79], v[216:217]
	v_pk_add_f32 v[76:77], v[76:77], v[214:215]
	v_cvt_pk_bf16_f32 v70, v100, v101
	v_cvt_pk_bf16_f32 v71, v102, v103
	global_store_dwordx4 v[162:163], v[68:71], off
	v_pk_add_f32 v[74:75], v[74:75], v[212:213]
	v_pk_add_f32 v[72:73], v[72:73], v[210:211]
	v_cvt_pk_bf16_f32 v68, v76, v77
	v_cvt_pk_bf16_f32 v69, v78, v79
	v_pk_add_f32 v[94:95], v[94:95], v[224:225]
	v_pk_add_f32 v[92:93], v[92:93], v[222:223]
	v_mad_i64_i32 v[124:125], s[42:43], v168, s41, v[150:151]
	v_cvt_pk_bf16_f32 v70, v72, v73
	v_cvt_pk_bf16_f32 v71, v74, v75
	global_store_dwordx4 v[162:163], v[68:71], off offset:256
	v_pk_add_f32 v[86:87], v[86:87], v[220:221]
	v_pk_add_f32 v[84:85], v[84:85], v[218:219]
	v_cvt_pk_bf16_f32 v68, v92, v93
	v_cvt_pk_bf16_f32 v69, v94, v95
	v_pk_add_f32 v[62:63], v[62:63], v[224:225]
	v_cvt_pk_bf16_f32 v70, v84, v85
	v_cvt_pk_bf16_f32 v71, v86, v87
	global_store_dwordx4 v[124:125], v[68:71], off
	v_pk_add_f32 v[60:61], v[60:61], v[222:223]
	v_pk_add_f32 v[52:53], v[52:53], v[214:215]
	v_pk_add_f32 v[68:69], v[66:67], v[212:213]
	v_pk_add_f32 v[66:67], v[64:65], v[210:211]
	v_cvt_pk_bf16_f32 v64, v166, v167
	v_cvt_pk_bf16_f32 v65, v164, v165
	v_pk_add_f32 v[54:55], v[54:55], v[216:217]
	v_cvt_pk_bf16_f32 v66, v66, v67
	v_cvt_pk_bf16_f32 v67, v68, v69
	global_store_dwordx4 v[124:125], v[64:67], off offset:256
	v_pk_add_f32 v[48:49], v[48:49], v[222:223]
	v_pk_add_f32 v[36:37], v[36:37], v[214:215]
	v_add_u32_e32 v64, 0x80, v157
	v_mad_i64_i32 v[64:65], s[42:43], v64, s41, v[150:151]
	v_pk_add_f32 v[66:67], v[58:59], v[220:221]
	v_pk_add_f32 v[58:59], v[56:57], v[218:219]
	v_cvt_pk_bf16_f32 v56, v60, v61
	v_cvt_pk_bf16_f32 v57, v62, v63
	v_pk_add_f32 v[38:39], v[38:39], v[216:217]
	v_cvt_pk_bf16_f32 v58, v58, v59
	v_cvt_pk_bf16_f32 v59, v66, v67
	global_store_dwordx4 v[64:65], v[56:59], off
	v_pk_add_f32 v[32:33], v[32:33], v[222:223]
	v_pk_add_f32 v[20:21], v[20:21], v[214:215]
	v_pk_add_f32 v[56:57], v[46:47], v[212:213]
	v_pk_add_f32 v[46:47], v[44:45], v[210:211]
	v_cvt_pk_bf16_f32 v44, v52, v53
	v_cvt_pk_bf16_f32 v45, v54, v55
	v_pk_add_f32 v[22:23], v[22:23], v[216:217]
	v_cvt_pk_bf16_f32 v46, v46, v47
	v_cvt_pk_bf16_f32 v47, v56, v57
	global_store_dwordx4 v[64:65], v[44:47], off offset:256
	v_pk_add_f32 v[16:17], v[16:17], v[222:223]
	v_pk_add_f32 v[6:7], v[6:7], v[216:217]
	v_add_u32_e32 v44, 0x90, v157
	v_mad_i64_i32 v[44:45], s[42:43], v44, s41, v[150:151]
	v_pk_add_f32 v[46:47], v[50:51], v[224:225]
	v_pk_add_f32 v[50:51], v[42:43], v[220:221]
	v_pk_add_f32 v[42:43], v[40:41], v[218:219]
	v_cvt_pk_bf16_f32 v40, v48, v49
	v_cvt_pk_bf16_f32 v41, v46, v47
	v_pk_add_f32 v[4:5], v[4:5], v[214:215]
	v_cvt_pk_bf16_f32 v42, v42, v43
	v_cvt_pk_bf16_f32 v43, v50, v51
	global_store_dwordx4 v[44:45], v[40:43], off
	s_nop 1
	v_pk_add_f32 v[40:41], v[30:31], v[212:213]
	v_pk_add_f32 v[30:31], v[28:29], v[210:211]
	v_cvt_pk_bf16_f32 v28, v36, v37
	v_cvt_pk_bf16_f32 v29, v38, v39
	s_nop 0
	v_cvt_pk_bf16_f32 v30, v30, v31
	v_cvt_pk_bf16_f32 v31, v40, v41
	global_store_dwordx4 v[44:45], v[28:31], off offset:256
	s_nop 1
	v_add_u32_e32 v28, 0xa0, v157
	v_mad_i64_i32 v[28:29], s[42:43], v28, s41, v[150:151]
	v_pk_add_f32 v[30:31], v[34:35], v[224:225]
	v_pk_add_f32 v[34:35], v[26:27], v[220:221]
	v_pk_add_f32 v[26:27], v[24:25], v[218:219]
	v_cvt_pk_bf16_f32 v24, v32, v33
	v_cvt_pk_bf16_f32 v25, v30, v31
	s_nop 0
	v_cvt_pk_bf16_f32 v26, v26, v27
	v_cvt_pk_bf16_f32 v27, v34, v35
	global_store_dwordx4 v[28:29], v[24:27], off
	s_nop 1
	v_pk_add_f32 v[24:25], v[14:15], v[212:213]
	v_pk_add_f32 v[14:15], v[12:13], v[210:211]
	v_cvt_pk_bf16_f32 v12, v20, v21
	v_cvt_pk_bf16_f32 v13, v22, v23
	s_nop 0
	v_cvt_pk_bf16_f32 v14, v14, v15
	v_cvt_pk_bf16_f32 v15, v24, v25
	global_store_dwordx4 v[28:29], v[12:15], off offset:256
	s_nop 1
	v_add_u32_e32 v12, 0xb0, v157
	v_mad_i64_i32 v[12:13], s[42:43], v12, s41, v[150:151]
	v_pk_add_f32 v[14:15], v[18:19], v[224:225]
	v_pk_add_f32 v[18:19], v[10:11], v[220:221]
	v_pk_add_f32 v[10:11], v[8:9], v[218:219]
	v_cvt_pk_bf16_f32 v8, v16, v17
	v_cvt_pk_bf16_f32 v9, v14, v15
	s_mov_b32 s42, s37
	v_cvt_pk_bf16_f32 v10, v10, v11
	v_cvt_pk_bf16_f32 v11, v18, v19
	global_store_dwordx4 v[12:13], v[8:11], off
	s_nop 1
	v_pk_add_f32 v[8:9], v[2:3], v[212:213]
	v_pk_add_f32 v[2:3], v[0:1], v[210:211]
	v_cvt_pk_bf16_f32 v0, v4, v5
	v_cvt_pk_bf16_f32 v1, v6, v7
	s_nop 0
	v_cvt_pk_bf16_f32 v2, v2, v3
	v_cvt_pk_bf16_f32 v3, v8, v9
	global_store_dwordx4 v[12:13], v[0:3], off offset:256
	s_mul_i32 s42, s42, s0
	s_add_i32 s42, s42, s1
	s_cmpk_gt_i32 s42, 0x4c7
	s_cbranch_scc1 .LBB0_281
	s_ashr_i32 s43, s42, 31
	s_lshr_b32 s43, s43, 29
	s_add_i32 s43, s42, s43
	s_ashr_i32 s44, s43, 3
	s_and_b32 s43, s43, -8
	s_sub_i32 s42, s42, s43
	s_cmp_lt_i32 s42, 0
	s_cselect_b32 s43, s38, 0x99
	s_mul_i32 s42, s43, s42
	s_add_i32 s42, s42, s44
	s_mul_hi_i32 s43, s42, 0x38e38e39
	s_lshr_b32 s44, s43, 31
	s_ashr_i32 s43, s43, 6
	s_add_i32 s43, s43, s44
	s_lshl_b32 s44, s43, 3
	s_sub_i32 s45, 34, s44
	s_min_u32 s45, s45, 8
	s_mulk_i32 s43, 0x120
	s_sub_i32 s46, s42, s43
	v_cvt_f32_ubyte0_e32 v1, s45
	v_cvt_f32_i32_e32 v0, s46
	v_rcp_iflag_f32_e32 v2, v1
	s_ashr_i32 s42, s46, 30
	s_or_b32 s47, s42, 1
	s_mov_b64 s[60:61], 0
	v_mul_f32_e32 v2, v0, v2
	v_trunc_f32_e32 v2, v2
	v_fma_f32 v0, -v2, v1, v0
	v_cvt_i32_f32_e32 v2, v2
	v_cmp_ge_f32_e64 s[42:43], |v0|, v1
	s_and_b64 s[42:43], s[42:43], exec
	s_cselect_b32 s42, s47, 0
	v_readfirstlane_b32 s43, v2
	s_add_i32 s42, s43, s42
	s_sext_i32_i16 s58, s42
	s_mul_i32 s42, s42, s45
	s_sub_i32 s42, s46, s42
	s_sext_i32_i16 s42, s42
	s_add_i32 s56, s44, s42
	s_lshl_b32 s44, s58, 8
	s_lshl_b32 s42, s36, 5
	s_add_i32 s42, s42, s44
	v_lshrrev_b32_e32 v226, 1, v152
	v_and_or_b32 v226, v226, 24, s42
	v_ashrrev_i32_e32 v227, 31, v226
	v_lshl_add_u64 v[226:227], v[226:227], 2, s[18:19]
	global_load_dwordx4 v[222:225], v[226:227], off
	global_load_dwordx4 v[218:221], v[226:227], off offset:16
	global_load_dwordx4 v[214:217], v[226:227], off offset:512
	global_load_dwordx4 v[210:213], v[226:227], off offset:528
	s_branch .LBB0_281

.LBB0_950:
	s_lshl_b32 s28, s38, 8
	s_lshl_b32 s29, s52, 5
	s_add_i32 s28, s28, s29
	v_lshrrev_b32_e32 v226, 1, v152
	v_and_or_b32 v226, v226, 24, s28
	v_ashrrev_i32_e32 v227, 31, v226
	v_lshl_add_u64 v[226:227], v[226:227], 2, s[18:19]
	global_load_dwordx4 v[222:225], v[226:227], off
	global_load_dwordx4 v[218:221], v[226:227], off offset:16
	global_load_dwordx4 v[214:217], v[226:227], off offset:512
	global_load_dwordx4 v[210:213], v[226:227], off offset:528
	s_add_i32 s57, s57, 1
	s_mul_i32 s29, s57, s0
	s_add_i32 s29, s29, s1
	s_cmpk_gt_i32 s29, 0x47f
	s_mov_b64 s[46:47], -1
	s_cbranch_scc0 .LBB0_953
	s_add_i32 s28, s29, 0xfffffb80
	s_cmp_gt_u32 s28, 3
	s_mov_b64 s[46:47], 0
	s_cbranch_scc1 .LBB0_963
	s_cmp_gt_u32 s28, 1
	s_cselect_b32 s2, 5, 4
	s_add_i32 s34, s29, 0xfffffb7e
	s_cmp_lt_u32 s28, 2
	s_cselect_b32 s28, s28, s34
	s_add_i32 s28, s28, 32
	s_mov_b64 s[34:35], -1
	s_mov_b64 s[44:45], s[2:3]

.LBB0_956:
	ds_read_b128 v[128:131], v154
	ds_read_b128 v[132:135], v154 offset:1024
	ds_read_b128 v[136:139], v154 offset:2048
	ds_read_b128 v[140:143], v154 offset:3072
	s_add_u32 s44, s40, 0xfff80080
	s_addc_u32 s45, s41, -1
	s_cmp_eq_u32 s43, 28
	s_cselect_b32 s45, s29, s45
	s_cselect_b32 s44, s28, s44
	s_cselect_b32 s47, s35, s42
	s_cselect_b32 s46, s34, s2
	v_lshl_add_u64 v[150:151], s[40:41], 0, v[148:149]
	s_add_i32 m0, s37, 0xc000
	ds_read_b128 v[158:161], v155
	ds_read_b128 v[162:165], v155 offset:1024
	ds_read_b128 v[166:169], v155 offset:2048
	ds_read_b128 v[170:173], v155 offset:3072
	ds_read_b128 v[174:177], v155 offset:4096
	ds_read_b128 v[178:181], v155 offset:5120
	ds_read_b128 v[182:185], v155 offset:6144
	ds_read_b128 v[186:189], v155 offset:7168
	global_load_lds_dwordx4 v[150:151], off
	v_lshl_add_u64 v[150:151], v[150:151], 0, s[6:7]
	s_add_i32 m0, s37, 0xe000
	s_nop 0
	global_load_lds_dwordx4 v[150:151], off
	s_waitcnt lgkmcnt(8)
	s_barrier
	s_waitcnt lgkmcnt(0)
	s_waitcnt lgkmcnt(0)
	v_mfma_f32_16x16x32_bf16 v[124:127], v[128:131], v[158:161], v[124:127]
	v_mfma_f32_16x16x32_bf16 v[120:123], v[136:139], v[158:161], v[120:123]
	v_mfma_f32_16x16x32_bf16 v[116:119], v[128:131], v[166:169], v[116:119]
	v_mfma_f32_16x16x32_bf16 v[112:115], v[136:139], v[166:169], v[112:115]
	v_mfma_f32_16x16x32_bf16 v[108:111], v[128:131], v[174:177], v[108:111]
	v_mfma_f32_16x16x32_bf16 v[100:103], v[136:139], v[174:177], v[100:103]
	v_mfma_f32_16x16x32_bf16 v[92:95], v[128:131], v[182:185], v[92:95]
	v_mfma_f32_16x16x32_bf16 v[80:83], v[136:139], v[182:185], v[80:83]
	v_mfma_f32_16x16x32_bf16 v[124:127], v[132:135], v[162:165], v[124:127]
	v_mfma_f32_16x16x32_bf16 v[120:123], v[140:143], v[162:165], v[120:123]
	v_mfma_f32_16x16x32_bf16 v[116:119], v[132:135], v[170:173], v[116:119]
	v_mfma_f32_16x16x32_bf16 v[112:115], v[140:143], v[170:173], v[112:115]
	v_mfma_f32_16x16x32_bf16 v[108:111], v[132:135], v[178:181], v[108:111]
	v_mfma_f32_16x16x32_bf16 v[100:103], v[140:143], v[178:181], v[100:103]
	v_mfma_f32_16x16x32_bf16 v[92:95], v[132:135], v[186:189], v[92:95]
	v_mfma_f32_16x16x32_bf16 v[80:83], v[140:143], v[186:189], v[80:83]
	s_barrier
	v_lshl_add_u64 v[150:151], s[46:47], 0, v[146:147]
	s_add_i32 s46, s54, s33
	s_mov_b32 m0, s46
	ds_read_b128 v[190:193], v156
	ds_read_b128 v[194:197], v156 offset:1024
	ds_read_b128 v[198:201], v156 offset:2048
	ds_read_b128 v[202:205], v156 offset:3072
	global_load_lds_dwordx4 v[150:151], off
	v_lshl_add_u64 v[206:207], v[150:151], 0, s[6:7]
	s_add_i32 m0, s46, 0x2000
	s_nop 0
	global_load_lds_dwordx4 v[206:207], off
	s_barrier
	s_waitcnt lgkmcnt(0)
	s_waitcnt lgkmcnt(0)
	v_mfma_f32_16x16x32_bf16 v[104:107], v[190:193], v[158:161], v[104:107]
	v_mfma_f32_16x16x32_bf16 v[96:99], v[198:201], v[158:161], v[96:99]
	v_mfma_f32_16x16x32_bf16 v[88:91], v[190:193], v[166:169], v[88:91]
	v_mfma_f32_16x16x32_bf16 v[84:87], v[198:201], v[166:169], v[84:87]
	v_mfma_f32_16x16x32_bf16 v[76:79], v[190:193], v[174:177], v[76:79]
	v_mfma_f32_16x16x32_bf16 v[72:75], v[198:201], v[174:177], v[72:75]
	v_mfma_f32_16x16x32_bf16 v[68:71], v[190:193], v[182:185], v[68:71]
	v_mfma_f32_16x16x32_bf16 v[64:67], v[198:201], v[182:185], v[64:67]
	v_mfma_f32_16x16x32_bf16 v[104:107], v[194:197], v[162:165], v[104:107]
	v_mfma_f32_16x16x32_bf16 v[96:99], v[202:205], v[162:165], v[96:99]
	v_mfma_f32_16x16x32_bf16 v[88:91], v[194:197], v[170:173], v[88:91]
	v_mfma_f32_16x16x32_bf16 v[84:87], v[202:205], v[170:173], v[84:87]
	v_mfma_f32_16x16x32_bf16 v[76:79], v[194:197], v[178:181], v[76:79]
	v_mfma_f32_16x16x32_bf16 v[72:75], v[202:205], v[178:181], v[72:75]
	v_mfma_f32_16x16x32_bf16 v[68:71], v[194:197], v[186:189], v[68:71]
	v_mfma_f32_16x16x32_bf16 v[64:67], v[202:205], v[186:189], v[64:67]
	s_mov_b32 m0, s37
	v_lshl_add_u64 v[206:207], s[44:45], 0, v[144:145]
	s_barrier
	ds_read_b128 v[158:161], v155 offset:16384
	ds_read_b128 v[162:165], v155 offset:17408
	ds_read_b128 v[166:169], v155 offset:18432
	ds_read_b128 v[170:173], v155 offset:19456
	ds_read_b128 v[174:177], v155 offset:20480
	ds_read_b128 v[178:181], v155 offset:21504
	ds_read_b128 v[182:185], v155 offset:22528
	ds_read_b128 v[186:189], v155 offset:23552
	global_load_lds_dwordx4 v[206:207], off
	v_lshl_add_u64 v[208:209], v[206:207], 0, s[6:7]
	s_mov_b32 m0, s39
	s_nop 0
	global_load_lds_dwordx4 v[208:209], off
	s_barrier
	s_waitcnt lgkmcnt(0)
	s_waitcnt lgkmcnt(0)
	v_mfma_f32_16x16x32_bf16 v[60:63], v[128:131], v[158:161], v[60:63]
	v_mfma_f32_16x16x32_bf16 v[56:59], v[136:139], v[158:161], v[56:59]
	v_mfma_f32_16x16x32_bf16 v[48:51], v[128:131], v[166:169], v[48:51]
	v_mfma_f32_16x16x32_bf16 v[40:43], v[136:139], v[166:169], v[40:43]
	v_mfma_f32_16x16x32_bf16 v[32:35], v[128:131], v[174:177], v[32:35]
	v_mfma_f32_16x16x32_bf16 v[24:27], v[136:139], v[174:177], v[24:27]
	v_mfma_f32_16x16x32_bf16 v[16:19], v[128:131], v[182:185], v[16:19]
	v_mfma_f32_16x16x32_bf16 v[8:11], v[136:139], v[182:185], v[8:11]
	v_mfma_f32_16x16x32_bf16 v[60:63], v[132:135], v[162:165], v[60:63]
	v_mfma_f32_16x16x32_bf16 v[56:59], v[140:143], v[162:165], v[56:59]
	v_mfma_f32_16x16x32_bf16 v[48:51], v[132:135], v[170:173], v[48:51]
	v_mfma_f32_16x16x32_bf16 v[40:43], v[140:143], v[170:173], v[40:43]
	v_mfma_f32_16x16x32_bf16 v[32:35], v[132:135], v[178:181], v[32:35]
	v_mfma_f32_16x16x32_bf16 v[24:27], v[140:143], v[178:181], v[24:27]
	v_mfma_f32_16x16x32_bf16 v[16:19], v[132:135], v[186:189], v[16:19]
	v_mfma_f32_16x16x32_bf16 v[8:11], v[140:143], v[186:189], v[8:11]
	s_barrier
	s_add_i32 s44, s55, s33
	v_lshl_add_u64 v[128:129], v[150:151], 0, s[8:9]
	s_mov_b32 m0, s44
	s_nop 0
	global_load_lds_dwordx4 v[128:129], off
	v_lshl_add_u64 v[128:129], v[150:151], 0, s[10:11]
	s_add_i32 m0, s44, 0x2000
	s_nop 0
	global_load_lds_dwordx4 v[128:129], off
	s_waitcnt vmcnt(6)
	s_barrier
	v_mfma_f32_16x16x32_bf16 v[52:55], v[190:193], v[158:161], v[52:55]
	v_mfma_f32_16x16x32_bf16 v[44:47], v[198:201], v[158:161], v[44:47]
	v_mfma_f32_16x16x32_bf16 v[36:39], v[190:193], v[166:169], v[36:39]
	v_mfma_f32_16x16x32_bf16 v[28:31], v[198:201], v[166:169], v[28:31]
	v_mfma_f32_16x16x32_bf16 v[20:23], v[190:193], v[174:177], v[20:23]
	v_mfma_f32_16x16x32_bf16 v[12:15], v[198:201], v[174:177], v[12:15]
	v_mfma_f32_16x16x32_bf16 v[4:7], v[190:193], v[182:185], v[4:7]
	v_mfma_f32_16x16x32_bf16 v[0:3], v[198:201], v[182:185], v[0:3]
	v_mfma_f32_16x16x32_bf16 v[52:55], v[194:197], v[162:165], v[52:55]
	v_mfma_f32_16x16x32_bf16 v[44:47], v[202:205], v[162:165], v[44:47]
	v_mfma_f32_16x16x32_bf16 v[36:39], v[194:197], v[170:173], v[36:39]
	v_mfma_f32_16x16x32_bf16 v[28:31], v[202:205], v[170:173], v[28:31]
	v_mfma_f32_16x16x32_bf16 v[20:23], v[194:197], v[178:181], v[20:23]
	v_mfma_f32_16x16x32_bf16 v[12:15], v[202:205], v[178:181], v[12:15]
	v_mfma_f32_16x16x32_bf16 v[4:7], v[194:197], v[186:189], v[4:7]
	v_mfma_f32_16x16x32_bf16 v[0:3], v[202:205], v[186:189], v[0:3]
	s_add_i32 s44, 0, 0x18000
	v_add_u32_e32 v140, s44, v153
	s_barrier
	ds_read_b128 v[128:131], v140
	ds_read_b128 v[132:135], v140 offset:1024
	ds_read_b128 v[136:139], v140 offset:2048
	ds_read_b128 v[140:143], v140 offset:3072
	s_mov_b32 m0, s48
	v_lshl_add_u64 v[190:191], v[206:207], 0, s[8:9]
	ds_read_b128 v[158:161], v155 offset:32768
	ds_read_b128 v[162:165], v155 offset:33792
	ds_read_b128 v[166:169], v155 offset:34816
	ds_read_b128 v[170:173], v155 offset:35840
	ds_read_b128 v[174:177], v155 offset:36864
	ds_read_b128 v[178:181], v155 offset:37888
	ds_read_b128 v[182:185], v155 offset:38912
	ds_read_b128 v[186:189], v155 offset:39936
	global_load_lds_dwordx4 v[190:191], off
	v_lshl_add_u64 v[190:191], v[206:207], 0, s[10:11]
	s_mov_b32 m0, s49
	s_nop 0
	global_load_lds_dwordx4 v[190:191], off
	s_waitcnt lgkmcnt(8)
	s_barrier
	s_waitcnt lgkmcnt(0)
	s_waitcnt lgkmcnt(0)
	v_mfma_f32_16x16x32_bf16 v[124:127], v[128:131], v[158:161], v[124:127]
	v_mfma_f32_16x16x32_bf16 v[120:123], v[136:139], v[158:161], v[120:123]
	v_mfma_f32_16x16x32_bf16 v[116:119], v[128:131], v[166:169], v[116:119]
	v_mfma_f32_16x16x32_bf16 v[112:115], v[136:139], v[166:169], v[112:115]
	v_mfma_f32_16x16x32_bf16 v[108:111], v[128:131], v[174:177], v[108:111]
	v_mfma_f32_16x16x32_bf16 v[100:103], v[136:139], v[174:177], v[100:103]
	v_mfma_f32_16x16x32_bf16 v[92:95], v[128:131], v[182:185], v[92:95]
	v_mfma_f32_16x16x32_bf16 v[80:83], v[136:139], v[182:185], v[80:83]
	v_mfma_f32_16x16x32_bf16 v[124:127], v[132:135], v[162:165], v[124:127]
	v_mfma_f32_16x16x32_bf16 v[120:123], v[140:143], v[162:165], v[120:123]
	v_mfma_f32_16x16x32_bf16 v[116:119], v[132:135], v[170:173], v[116:119]
	v_mfma_f32_16x16x32_bf16 v[112:115], v[140:143], v[170:173], v[112:115]
	v_mfma_f32_16x16x32_bf16 v[108:111], v[132:135], v[178:181], v[108:111]
	v_mfma_f32_16x16x32_bf16 v[100:103], v[140:143], v[178:181], v[100:103]
	v_mfma_f32_16x16x32_bf16 v[92:95], v[132:135], v[186:189], v[92:95]
	v_mfma_f32_16x16x32_bf16 v[80:83], v[140:143], v[186:189], v[80:83]
	s_barrier
	s_add_i32 s45, 0, 0x1c000
	s_add_i32 s44, s44, s33
	v_add_u32_e32 v157, s45, v153
	v_lshl_add_u64 v[208:209], v[150:151], 0, s[20:21]
	s_mov_b32 m0, s44
	ds_read_b128 v[190:193], v157
	ds_read_b128 v[194:197], v157 offset:1024
	ds_read_b128 v[198:201], v157 offset:2048
	ds_read_b128 v[202:205], v157 offset:3072
	global_load_lds_dwordx4 v[208:209], off
	v_lshl_add_u64 v[208:209], v[150:151], 0, s[22:23]
	s_add_i32 m0, s44, 0x2000
	s_nop 0
	global_load_lds_dwordx4 v[208:209], off
	s_barrier
	s_waitcnt lgkmcnt(0)
	s_waitcnt lgkmcnt(0)
	v_mfma_f32_16x16x32_bf16 v[104:107], v[190:193], v[158:161], v[104:107]
	v_mfma_f32_16x16x32_bf16 v[96:99], v[198:201], v[158:161], v[96:99]
	v_mfma_f32_16x16x32_bf16 v[88:91], v[190:193], v[166:169], v[88:91]
	v_mfma_f32_16x16x32_bf16 v[84:87], v[198:201], v[166:169], v[84:87]
	v_mfma_f32_16x16x32_bf16 v[76:79], v[190:193], v[174:177], v[76:79]
	v_mfma_f32_16x16x32_bf16 v[72:75], v[198:201], v[174:177], v[72:75]
	v_mfma_f32_16x16x32_bf16 v[68:71], v[190:193], v[182:185], v[68:71]
	v_mfma_f32_16x16x32_bf16 v[64:67], v[198:201], v[182:185], v[64:67]
	v_mfma_f32_16x16x32_bf16 v[104:107], v[194:197], v[162:165], v[104:107]
	v_mfma_f32_16x16x32_bf16 v[96:99], v[202:205], v[162:165], v[96:99]
	v_mfma_f32_16x16x32_bf16 v[88:91], v[194:197], v[170:173], v[88:91]
	v_mfma_f32_16x16x32_bf16 v[84:87], v[202:205], v[170:173], v[84:87]
	v_mfma_f32_16x16x32_bf16 v[76:79], v[194:197], v[178:181], v[76:79]
	v_mfma_f32_16x16x32_bf16 v[72:75], v[202:205], v[178:181], v[72:75]
	v_mfma_f32_16x16x32_bf16 v[68:71], v[194:197], v[186:189], v[68:71]
	v_mfma_f32_16x16x32_bf16 v[64:67], v[202:205], v[186:189], v[64:67]
	s_mov_b32 m0, s50
	v_lshl_add_u64 v[208:209], v[206:207], 0, s[20:21]
	s_barrier
	ds_read_b128 v[158:161], v155 offset:49152
	ds_read_b128 v[162:165], v155 offset:50176
	ds_read_b128 v[166:169], v155 offset:51200
	ds_read_b128 v[170:173], v155 offset:52224
	ds_read_b128 v[174:177], v155 offset:53248
	ds_read_b128 v[178:181], v155 offset:54272
	ds_read_b128 v[182:185], v155 offset:55296
	ds_read_b128 v[186:189], v155 offset:56320
	global_load_lds_dwordx4 v[208:209], off
	v_lshl_add_u64 v[206:207], v[206:207], 0, s[22:23]
	s_mov_b32 m0, s51
	s_nop 0
	global_load_lds_dwordx4 v[206:207], off
	s_barrier
	s_waitcnt lgkmcnt(0)
	s_waitcnt lgkmcnt(0)
	v_mfma_f32_16x16x32_bf16 v[60:63], v[128:131], v[158:161], v[60:63]
	v_mfma_f32_16x16x32_bf16 v[56:59], v[136:139], v[158:161], v[56:59]
	v_mfma_f32_16x16x32_bf16 v[48:51], v[128:131], v[166:169], v[48:51]
	v_mfma_f32_16x16x32_bf16 v[40:43], v[136:139], v[166:169], v[40:43]
	v_mfma_f32_16x16x32_bf16 v[32:35], v[128:131], v[174:177], v[32:35]
	v_mfma_f32_16x16x32_bf16 v[24:27], v[136:139], v[174:177], v[24:27]
	v_mfma_f32_16x16x32_bf16 v[16:19], v[128:131], v[182:185], v[16:19]
	v_mfma_f32_16x16x32_bf16 v[8:11], v[136:139], v[182:185], v[8:11]
	v_mfma_f32_16x16x32_bf16 v[60:63], v[132:135], v[162:165], v[60:63]
	v_mfma_f32_16x16x32_bf16 v[56:59], v[140:143], v[162:165], v[56:59]
	v_mfma_f32_16x16x32_bf16 v[48:51], v[132:135], v[170:173], v[48:51]
	v_mfma_f32_16x16x32_bf16 v[40:43], v[140:143], v[170:173], v[40:43]
	v_mfma_f32_16x16x32_bf16 v[32:35], v[132:135], v[178:181], v[32:35]
	v_mfma_f32_16x16x32_bf16 v[24:27], v[140:143], v[178:181], v[24:27]
	v_mfma_f32_16x16x32_bf16 v[16:19], v[132:135], v[186:189], v[16:19]
	v_mfma_f32_16x16x32_bf16 v[8:11], v[140:143], v[186:189], v[8:11]
	s_barrier
	s_add_i32 s44, s45, s33
	v_lshl_add_u64 v[128:129], v[150:151], 0, s[24:25]
	s_mov_b32 m0, s44
	s_nop 0
	global_load_lds_dwordx4 v[128:129], off
	v_lshl_add_u64 v[128:129], v[150:151], 0, s[26:27]
	s_add_i32 m0, s44, 0x2000
	s_nop 0
	global_load_lds_dwordx4 v[128:129], off
	s_waitcnt vmcnt(6)
	s_barrier
	v_mfma_f32_16x16x32_bf16 v[52:55], v[190:193], v[158:161], v[52:55]
	v_mfma_f32_16x16x32_bf16 v[44:47], v[198:201], v[158:161], v[44:47]
	v_mfma_f32_16x16x32_bf16 v[36:39], v[190:193], v[166:169], v[36:39]
	v_mfma_f32_16x16x32_bf16 v[28:31], v[198:201], v[166:169], v[28:31]
	v_mfma_f32_16x16x32_bf16 v[20:23], v[190:193], v[174:177], v[20:23]
	v_mfma_f32_16x16x32_bf16 v[12:15], v[198:201], v[174:177], v[12:15]
	v_mfma_f32_16x16x32_bf16 v[4:7], v[190:193], v[182:185], v[4:7]
	v_mfma_f32_16x16x32_bf16 v[0:3], v[198:201], v[182:185], v[0:3]
	v_mfma_f32_16x16x32_bf16 v[52:55], v[194:197], v[162:165], v[52:55]
	v_mfma_f32_16x16x32_bf16 v[44:47], v[202:205], v[162:165], v[44:47]
	v_mfma_f32_16x16x32_bf16 v[36:39], v[194:197], v[170:173], v[36:39]
	v_mfma_f32_16x16x32_bf16 v[28:31], v[202:205], v[170:173], v[28:31]
	v_mfma_f32_16x16x32_bf16 v[20:23], v[194:197], v[178:181], v[20:23]
	v_mfma_f32_16x16x32_bf16 v[12:15], v[202:205], v[178:181], v[12:15]
	v_mfma_f32_16x16x32_bf16 v[4:7], v[194:197], v[186:189], v[4:7]
	v_mfma_f32_16x16x32_bf16 v[0:3], v[202:205], v[186:189], v[0:3]
	s_add_i32 s43, s43, 2
	s_add_u32 s40, s40, 0x100
	s_addc_u32 s41, s41, 0
	s_add_u32 s2, s2, 0x100
	s_addc_u32 s42, s42, 0
	s_cmp_gt_u32 s43, 29
	s_barrier
	s_cbranch_scc0 .LBB0_956
	v_mov_b32_e32 v157, v152
	s_mov_b32 s2, s52
	s_mov_b32 s40, s31
	s_lshl_b32 s38, s38, 8
	s_lshl_b32 s2, s2, 5
	s_add_i32 s2, s2, s38
	v_lshrrev_b32_e32 v128, 1, v157
	v_and_or_b32 v150, v128, 24, s2
	v_ashrrev_i32_e32 v151, 31, v150
	s_lshl_b32 s2, s36, 8
	v_and_or_b32 v157, v157, 15, s2
	v_lshl_add_u32 v157, s40, 6, v157
	v_lshl_add_u64 v[150:151], v[150:151], 1, s[16:17]
	v_mad_i64_i32 v[158:159], s[40:41], v157, s56, v[150:151]
	v_or_b32_e32 v160, 16, v157
	v_mad_i64_i32 v[160:161], s[40:41], v160, s56, v[150:151]
	v_or_b32_e32 v162, 32, v157
	v_mad_i64_i32 v[162:163], s[40:41], v162, s56, v[150:151]
	v_or_b32_e32 v164, 48, v157
	v_mad_i64_i32 v[164:165], s[40:41], v164, s56, v[150:151]
	s_mov_b32 s2, s57
	v_pk_add_f32 v[126:127], v[126:127], v[224:225]
	v_pk_add_f32 v[124:125], v[124:125], v[222:223]
	v_pk_add_f32 v[168:169], v[68:69], v[214:215]
	v_cvt_pk_bf16_f32 v68, v124, v125
	v_cvt_pk_bf16_f32 v69, v126, v127
	v_pk_add_f32 v[122:123], v[122:123], v[220:221]
	v_pk_add_f32 v[120:121], v[120:121], v[218:219]
	v_pk_add_f32 v[106:107], v[106:107], v[216:217]
	v_pk_add_f32 v[104:105], v[104:105], v[214:215]
	v_pk_add_f32 v[166:167], v[70:71], v[216:217]
	v_cvt_pk_bf16_f32 v70, v120, v121
	v_cvt_pk_bf16_f32 v71, v122, v123
	global_store_dwordx4 v[158:159], v[68:71], off
	v_pk_add_f32 v[98:99], v[98:99], v[212:213]
	v_pk_add_f32 v[96:97], v[96:97], v[210:211]
	v_cvt_pk_bf16_f32 v68, v104, v105
	v_cvt_pk_bf16_f32 v69, v106, v107
	v_pk_add_f32 v[118:119], v[118:119], v[224:225]
	v_pk_add_f32 v[116:117], v[116:117], v[222:223]
	v_cvt_pk_bf16_f32 v70, v96, v97
	v_cvt_pk_bf16_f32 v71, v98, v99
	global_store_dwordx4 v[158:159], v[68:71], off offset:256
	v_pk_add_f32 v[114:115], v[114:115], v[220:221]
	v_pk_add_f32 v[112:113], v[112:113], v[218:219]
	v_cvt_pk_bf16_f32 v68, v116, v117
	v_cvt_pk_bf16_f32 v69, v118, v119
	v_pk_add_f32 v[90:91], v[90:91], v[216:217]
	v_pk_add_f32 v[88:89], v[88:89], v[214:215]
	v_cvt_pk_bf16_f32 v70, v112, v113
	v_cvt_pk_bf16_f32 v71, v114, v115
	global_store_dwordx4 v[160:161], v[68:71], off
	v_pk_add_f32 v[86:87], v[86:87], v[212:213]
	v_pk_add_f32 v[84:85], v[84:85], v[210:211]
	v_cvt_pk_bf16_f32 v68, v88, v89
	v_cvt_pk_bf16_f32 v69, v90, v91
	v_pk_add_f32 v[110:111], v[110:111], v[224:225]
	v_pk_add_f32 v[108:109], v[108:109], v[222:223]
	v_cvt_pk_bf16_f32 v70, v84, v85
	v_cvt_pk_bf16_f32 v71, v86, v87
	global_store_dwordx4 v[160:161], v[68:71], off offset:256
	v_pk_add_f32 v[102:103], v[102:103], v[220:221]
	v_pk_add_f32 v[100:101], v[100:101], v[218:219]
	v_cvt_pk_bf16_f32 v68, v108, v109
	v_cvt_pk_bf16_f32 v69, v110, v111
	v_pk_add_f32 v[78:79], v[78:79], v[216:217]
	v_pk_add_f32 v[76:77], v[76:77], v[214:215]
	v_cvt_pk_bf16_f32 v70, v100, v101
	v_cvt_pk_bf16_f32 v71, v102, v103
	global_store_dwordx4 v[162:163], v[68:71], off
	v_pk_add_f32 v[74:75], v[74:75], v[212:213]
	v_pk_add_f32 v[72:73], v[72:73], v[210:211]
	v_cvt_pk_bf16_f32 v68, v76, v77
	v_cvt_pk_bf16_f32 v69, v78, v79
	v_pk_add_f32 v[94:95], v[94:95], v[224:225]
	v_pk_add_f32 v[92:93], v[92:93], v[222:223]
	v_cvt_pk_bf16_f32 v70, v72, v73
	v_cvt_pk_bf16_f32 v71, v74, v75
	global_store_dwordx4 v[162:163], v[68:71], off offset:256
	v_pk_add_f32 v[82:83], v[82:83], v[220:221]
	v_pk_add_f32 v[80:81], v[80:81], v[218:219]
	v_cvt_pk_bf16_f32 v68, v92, v93
	v_cvt_pk_bf16_f32 v69, v94, v95
	v_pk_add_f32 v[62:63], v[62:63], v[224:225]
	v_cvt_pk_bf16_f32 v70, v80, v81
	v_cvt_pk_bf16_f32 v71, v82, v83
	global_store_dwordx4 v[164:165], v[68:71], off
	v_pk_add_f32 v[60:61], v[60:61], v[222:223]
	v_pk_add_f32 v[52:53], v[52:53], v[214:215]
	v_pk_add_f32 v[68:69], v[66:67], v[212:213]
	v_pk_add_f32 v[66:67], v[64:65], v[210:211]
	v_cvt_pk_bf16_f32 v64, v168, v169
	v_cvt_pk_bf16_f32 v65, v166, v167
	v_pk_add_f32 v[54:55], v[54:55], v[216:217]
	v_cvt_pk_bf16_f32 v66, v66, v67
	v_cvt_pk_bf16_f32 v67, v68, v69
	global_store_dwordx4 v[164:165], v[64:67], off offset:256
	v_pk_add_f32 v[48:49], v[48:49], v[222:223]
	v_pk_add_f32 v[36:37], v[36:37], v[214:215]
	v_add_u32_e32 v64, 0x80, v157
	v_mad_i64_i32 v[64:65], s[40:41], v64, s56, v[150:151]
	v_pk_add_f32 v[66:67], v[58:59], v[220:221]
	v_pk_add_f32 v[58:59], v[56:57], v[218:219]
	v_cvt_pk_bf16_f32 v56, v60, v61
	v_cvt_pk_bf16_f32 v57, v62, v63
	v_pk_add_f32 v[38:39], v[38:39], v[216:217]
	v_cvt_pk_bf16_f32 v58, v58, v59
	v_cvt_pk_bf16_f32 v59, v66, v67
	global_store_dwordx4 v[64:65], v[56:59], off
	v_pk_add_f32 v[32:33], v[32:33], v[222:223]
	v_pk_add_f32 v[20:21], v[20:21], v[214:215]
	v_pk_add_f32 v[56:57], v[46:47], v[212:213]
	v_pk_add_f32 v[46:47], v[44:45], v[210:211]
	v_cvt_pk_bf16_f32 v44, v52, v53
	v_cvt_pk_bf16_f32 v45, v54, v55
	v_pk_add_f32 v[22:23], v[22:23], v[216:217]
	v_cvt_pk_bf16_f32 v46, v46, v47
	v_cvt_pk_bf16_f32 v47, v56, v57
	global_store_dwordx4 v[64:65], v[44:47], off offset:256
	v_pk_add_f32 v[16:17], v[16:17], v[222:223]
	v_pk_add_f32 v[6:7], v[6:7], v[216:217]
	v_add_u32_e32 v44, 0x90, v157
	v_mad_i64_i32 v[44:45], s[40:41], v44, s56, v[150:151]
	v_pk_add_f32 v[46:47], v[50:51], v[224:225]
	v_pk_add_f32 v[50:51], v[42:43], v[220:221]
	v_pk_add_f32 v[42:43], v[40:41], v[218:219]
	v_cvt_pk_bf16_f32 v40, v48, v49
	v_cvt_pk_bf16_f32 v41, v46, v47
	v_pk_add_f32 v[4:5], v[4:5], v[214:215]
	v_cvt_pk_bf16_f32 v42, v42, v43
	v_cvt_pk_bf16_f32 v43, v50, v51
	global_store_dwordx4 v[44:45], v[40:43], off
	s_nop 1
	v_pk_add_f32 v[40:41], v[30:31], v[212:213]
	v_pk_add_f32 v[30:31], v[28:29], v[210:211]
	v_cvt_pk_bf16_f32 v28, v36, v37
	v_cvt_pk_bf16_f32 v29, v38, v39
	s_nop 0
	v_cvt_pk_bf16_f32 v30, v30, v31
	v_cvt_pk_bf16_f32 v31, v40, v41
	global_store_dwordx4 v[44:45], v[28:31], off offset:256
	s_nop 1
	v_add_u32_e32 v28, 0xa0, v157
	v_mad_i64_i32 v[28:29], s[40:41], v28, s56, v[150:151]
	v_pk_add_f32 v[30:31], v[34:35], v[224:225]
	v_pk_add_f32 v[34:35], v[26:27], v[220:221]
	v_pk_add_f32 v[26:27], v[24:25], v[218:219]
	v_cvt_pk_bf16_f32 v24, v32, v33
	v_cvt_pk_bf16_f32 v25, v30, v31
	s_nop 0
	v_cvt_pk_bf16_f32 v26, v26, v27
	v_cvt_pk_bf16_f32 v27, v34, v35
	global_store_dwordx4 v[28:29], v[24:27], off
	s_nop 1
	v_pk_add_f32 v[24:25], v[14:15], v[212:213]
	v_pk_add_f32 v[14:15], v[12:13], v[210:211]
	v_cvt_pk_bf16_f32 v12, v20, v21
	v_cvt_pk_bf16_f32 v13, v22, v23
	s_nop 0
	v_cvt_pk_bf16_f32 v14, v14, v15
	v_cvt_pk_bf16_f32 v15, v24, v25
	global_store_dwordx4 v[28:29], v[12:15], off offset:256
	s_nop 1
	v_add_u32_e32 v12, 0xb0, v157
	v_mad_i64_i32 v[12:13], s[40:41], v12, s56, v[150:151]
	v_pk_add_f32 v[14:15], v[18:19], v[224:225]
	v_pk_add_f32 v[18:19], v[10:11], v[220:221]
	v_pk_add_f32 v[10:11], v[8:9], v[218:219]
	v_cvt_pk_bf16_f32 v8, v16, v17
	v_cvt_pk_bf16_f32 v9, v14, v15
	s_mov_b64 s[40:41], -1
	v_cvt_pk_bf16_f32 v10, v10, v11
	v_cvt_pk_bf16_f32 v11, v18, v19
	global_store_dwordx4 v[12:13], v[8:11], off
	s_nop 1
	v_pk_add_f32 v[8:9], v[2:3], v[212:213]
	v_pk_add_f32 v[2:3], v[0:1], v[210:211]
	v_cvt_pk_bf16_f32 v0, v4, v5
	v_cvt_pk_bf16_f32 v1, v6, v7
	s_nop 0
	v_cvt_pk_bf16_f32 v2, v2, v3
	v_cvt_pk_bf16_f32 v3, v8, v9
	global_store_dwordx4 v[12:13], v[0:3], off offset:256
	s_mul_i32 s2, s2, s0
	s_add_i32 s2, s2, s1
	s_cmpk_gt_i32 s2, 0x47f
	s_cbranch_scc0 .LBB0_961
	s_andn2_b64 vcc, exec, s[40:41]
	s_cbranch_vccnz .LBB0_962
